# EpiQKV0 epilogue: lane pairs exchange halves (permlane16_swap) so each lane stores 16 B (64 B row segments), loads upfront, no waits between stores
# speedup vs baseline: 1.0195x; 1.0057x over previous
.LBB0_107:
	ds_read_b128 v[128:131], v170
	ds_read_b128 v[132:135], v170 offset:1024
	ds_read_b128 v[152:155], v170 offset:2048
	ds_read_b128 v[156:159], v170 offset:3072
	s_add_u32 s16, s14, 0xfff80080
	s_addc_u32 s17, s15, -1
	s_cmp_eq_u32 s81, 28
	s_cselect_b32 s19, s9, s17
	s_cselect_b32 s18, s13, s16
	s_cselect_b32 s17, s49, s69
	s_cselect_b32 s16, s55, s68
	v_lshl_add_u64 v[202:203], s[14:15], 0, v[144:145]
	s_add_i32 m0, s26, 0xc000
	ds_read_b128 v[160:163], v171
	ds_read_b128 v[174:177], v171 offset:1024
	ds_read_b128 v[178:181], v171 offset:2048
	ds_read_b128 v[182:185], v171 offset:3072
	ds_read_b128 v[186:189], v171 offset:4096
	ds_read_b128 v[190:193], v171 offset:5120
	ds_read_b128 v[194:197], v171 offset:6144
	ds_read_b128 v[198:201], v171 offset:7168
	global_load_lds_dwordx4 v[202:203], off
	v_lshl_add_u64 v[202:203], s[14:15], 0, v[146:147]
	s_add_i32 m0, s26, 0xe000
	s_nop 0
	global_load_lds_dwordx4 v[202:203], off
	s_waitcnt lgkmcnt(8)
	s_barrier
	s_waitcnt lgkmcnt(0)
	s_setprio 1
	s_waitcnt lgkmcnt(0)
	v_mfma_f32_16x16x32_bf16 v[124:127], v[128:131], v[160:163], v[124:127]
	v_mfma_f32_16x16x32_bf16 v[120:123], v[152:155], v[160:163], v[120:123]
	v_mfma_f32_16x16x32_bf16 v[108:111], v[128:131], v[178:181], v[108:111]
	v_mfma_f32_16x16x32_bf16 v[104:107], v[152:155], v[178:181], v[104:107]
	v_mfma_f32_16x16x32_bf16 v[92:95], v[128:131], v[186:189], v[92:95]
	v_mfma_f32_16x16x32_bf16 v[88:91], v[152:155], v[186:189], v[88:91]
	v_mfma_f32_16x16x32_bf16 v[76:79], v[128:131], v[194:197], v[76:79]
	v_mfma_f32_16x16x32_bf16 v[72:75], v[152:155], v[194:197], v[72:75]
	v_mfma_f32_16x16x32_bf16 v[124:127], v[132:135], v[174:177], v[124:127]
	v_mfma_f32_16x16x32_bf16 v[120:123], v[156:159], v[174:177], v[120:123]
	v_mfma_f32_16x16x32_bf16 v[108:111], v[132:135], v[182:185], v[108:111]
	v_mfma_f32_16x16x32_bf16 v[104:107], v[156:159], v[182:185], v[104:107]
	v_mfma_f32_16x16x32_bf16 v[92:95], v[132:135], v[190:193], v[92:95]
	v_mfma_f32_16x16x32_bf16 v[88:91], v[156:159], v[190:193], v[88:91]
	v_mfma_f32_16x16x32_bf16 v[76:79], v[132:135], v[198:201], v[76:79]
	v_mfma_f32_16x16x32_bf16 v[72:75], v[156:159], v[198:201], v[72:75]
	s_setprio 0
	s_barrier
	s_add_i32 s82, s72, s5
	v_lshl_add_u64 v[218:219], s[16:17], 0, v[138:139]
	s_mov_b32 m0, s82
	ds_read_b128 v[202:205], v172
	ds_read_b128 v[206:209], v172 offset:1024
	ds_read_b128 v[210:213], v172 offset:2048
	ds_read_b128 v[214:217], v172 offset:3072
	global_load_lds_dwordx4 v[218:219], off
	v_lshl_add_u64 v[220:221], s[16:17], 0, v[140:141]
	s_add_i32 m0, s82, 0x2000
	s_nop 0
	global_load_lds_dwordx4 v[220:221], off
	s_barrier
	s_waitcnt lgkmcnt(0)
	s_setprio 1
	s_waitcnt lgkmcnt(0)
	v_mfma_f32_16x16x32_bf16 v[116:119], v[202:205], v[160:163], v[116:119]
	v_mfma_f32_16x16x32_bf16 v[112:115], v[210:213], v[160:163], v[112:115]
	v_mfma_f32_16x16x32_bf16 v[100:103], v[202:205], v[178:181], v[100:103]
	v_mfma_f32_16x16x32_bf16 v[96:99], v[210:213], v[178:181], v[96:99]
	v_mfma_f32_16x16x32_bf16 v[84:87], v[202:205], v[186:189], v[84:87]
	v_mfma_f32_16x16x32_bf16 v[80:83], v[210:213], v[186:189], v[80:83]
	v_mfma_f32_16x16x32_bf16 v[68:71], v[202:205], v[194:197], v[68:71]
	v_mfma_f32_16x16x32_bf16 v[64:67], v[210:213], v[194:197], v[64:67]
	v_mfma_f32_16x16x32_bf16 v[116:119], v[206:209], v[174:177], v[116:119]
	v_mfma_f32_16x16x32_bf16 v[112:115], v[214:217], v[174:177], v[112:115]
	v_mfma_f32_16x16x32_bf16 v[100:103], v[206:209], v[182:185], v[100:103]
	v_mfma_f32_16x16x32_bf16 v[96:99], v[214:217], v[182:185], v[96:99]
	v_mfma_f32_16x16x32_bf16 v[84:87], v[206:209], v[190:193], v[84:87]
	v_mfma_f32_16x16x32_bf16 v[80:83], v[214:217], v[190:193], v[80:83]
	v_mfma_f32_16x16x32_bf16 v[68:71], v[206:209], v[198:201], v[68:71]
	v_mfma_f32_16x16x32_bf16 v[64:67], v[214:217], v[198:201], v[64:67]
	s_setprio 0
	s_mov_b32 m0, s26
	v_lshl_add_u64 v[222:223], s[18:19], 0, v[138:139]
	s_barrier
	ds_read_b128 v[160:163], v171 offset:16384
	ds_read_b128 v[174:177], v171 offset:17408
	ds_read_b128 v[178:181], v171 offset:18432
	ds_read_b128 v[182:185], v171 offset:19456
	ds_read_b128 v[186:189], v171 offset:20480
	ds_read_b128 v[190:193], v171 offset:21504
	ds_read_b128 v[194:197], v171 offset:22528
	ds_read_b128 v[198:201], v171 offset:23552
	global_load_lds_dwordx4 v[222:223], off
	v_lshl_add_u64 v[224:225], s[18:19], 0, v[140:141]
	s_mov_b32 m0, s27
	s_nop 0
	global_load_lds_dwordx4 v[224:225], off
	s_barrier
	s_waitcnt lgkmcnt(0)
	s_setprio 1
	s_waitcnt lgkmcnt(0)
	v_mfma_f32_16x16x32_bf16 v[60:63], v[128:131], v[160:163], v[60:63]
	v_mfma_f32_16x16x32_bf16 v[56:59], v[152:155], v[160:163], v[56:59]
	v_mfma_f32_16x16x32_bf16 v[44:47], v[128:131], v[178:181], v[44:47]
	v_mfma_f32_16x16x32_bf16 v[40:43], v[152:155], v[178:181], v[40:43]
	v_mfma_f32_16x16x32_bf16 v[28:31], v[128:131], v[186:189], v[28:31]
	v_mfma_f32_16x16x32_bf16 v[24:27], v[152:155], v[186:189], v[24:27]
	v_mfma_f32_16x16x32_bf16 v[12:15], v[128:131], v[194:197], v[12:15]
	v_mfma_f32_16x16x32_bf16 v[8:11], v[152:155], v[194:197], v[8:11]
	v_mfma_f32_16x16x32_bf16 v[60:63], v[132:135], v[174:177], v[60:63]
	v_mfma_f32_16x16x32_bf16 v[56:59], v[156:159], v[174:177], v[56:59]
	v_mfma_f32_16x16x32_bf16 v[44:47], v[132:135], v[182:185], v[44:47]
	v_mfma_f32_16x16x32_bf16 v[40:43], v[156:159], v[182:185], v[40:43]
	v_mfma_f32_16x16x32_bf16 v[28:31], v[132:135], v[190:193], v[28:31]
	v_mfma_f32_16x16x32_bf16 v[24:27], v[156:159], v[190:193], v[24:27]
	v_mfma_f32_16x16x32_bf16 v[12:15], v[132:135], v[198:201], v[12:15]
	v_mfma_f32_16x16x32_bf16 v[8:11], v[156:159], v[198:201], v[8:11]
	s_setprio 0
	s_barrier
	s_add_u32 s82, s16, 0x80000
	s_addc_u32 s83, s17, 0
	s_add_i32 s84, s73, s5
	v_lshl_add_u64 v[128:129], s[82:83], 0, v[138:139]
	s_mov_b32 m0, s84
	s_nop 0
	global_load_lds_dwordx4 v[128:129], off
	v_lshl_add_u64 v[128:129], s[82:83], 0, v[140:141]
	s_add_i32 m0, s84, 0x2000
	s_nop 0
	global_load_lds_dwordx4 v[128:129], off
	s_waitcnt vmcnt(6)
	s_barrier
	s_setprio 1
	v_mfma_f32_16x16x32_bf16 v[52:55], v[202:205], v[160:163], v[52:55]
	v_mfma_f32_16x16x32_bf16 v[48:51], v[210:213], v[160:163], v[48:51]
	v_mfma_f32_16x16x32_bf16 v[36:39], v[202:205], v[178:181], v[36:39]
	v_mfma_f32_16x16x32_bf16 v[32:35], v[210:213], v[178:181], v[32:35]
	v_mfma_f32_16x16x32_bf16 v[20:23], v[202:205], v[186:189], v[20:23]
	v_mfma_f32_16x16x32_bf16 v[16:19], v[210:213], v[186:189], v[16:19]
	v_mfma_f32_16x16x32_bf16 v[4:7], v[202:205], v[194:197], v[4:7]
	v_mfma_f32_16x16x32_bf16 v[0:3], v[210:213], v[194:197], v[0:3]
	v_mfma_f32_16x16x32_bf16 v[52:55], v[206:209], v[174:177], v[52:55]
	v_mfma_f32_16x16x32_bf16 v[48:51], v[214:217], v[174:177], v[48:51]
	v_mfma_f32_16x16x32_bf16 v[36:39], v[206:209], v[182:185], v[36:39]
	v_mfma_f32_16x16x32_bf16 v[32:35], v[214:217], v[182:185], v[32:35]
	v_mfma_f32_16x16x32_bf16 v[20:23], v[206:209], v[190:193], v[20:23]
	v_mfma_f32_16x16x32_bf16 v[16:19], v[214:217], v[190:193], v[16:19]
	v_mfma_f32_16x16x32_bf16 v[4:7], v[206:209], v[198:201], v[4:7]
	v_mfma_f32_16x16x32_bf16 v[0:3], v[214:217], v[198:201], v[0:3]
	s_setprio 0
	s_add_i32 s82, 16, 0x18000
	v_add_u32_e32 v156, s82, v166
	s_barrier
	ds_read_b128 v[128:131], v156
	ds_read_b128 v[132:135], v156 offset:1024
	ds_read_b128 v[152:155], v156 offset:2048
	ds_read_b128 v[156:159], v156 offset:3072
	s_add_u32 s18, s18, 0x80000
	s_addc_u32 s19, s19, 0
	s_mov_b32 m0, s39
	v_lshl_add_u64 v[202:203], s[18:19], 0, v[138:139]
	ds_read_b128 v[160:163], v171 offset:32768
	ds_read_b128 v[174:177], v171 offset:33792
	ds_read_b128 v[178:181], v171 offset:34816
	ds_read_b128 v[182:185], v171 offset:35840
	ds_read_b128 v[186:189], v171 offset:36864
	ds_read_b128 v[190:193], v171 offset:37888
	ds_read_b128 v[194:197], v171 offset:38912
	ds_read_b128 v[198:201], v171 offset:39936
	global_load_lds_dwordx4 v[202:203], off
	v_lshl_add_u64 v[202:203], s[18:19], 0, v[140:141]
	s_mov_b32 m0, s47
	s_nop 0
	global_load_lds_dwordx4 v[202:203], off
	s_waitcnt lgkmcnt(8)
	s_barrier
	s_waitcnt lgkmcnt(0)
	s_setprio 1
	s_waitcnt lgkmcnt(0)
	v_mfma_f32_16x16x32_bf16 v[124:127], v[128:131], v[160:163], v[124:127]
	v_mfma_f32_16x16x32_bf16 v[120:123], v[152:155], v[160:163], v[120:123]
	v_mfma_f32_16x16x32_bf16 v[108:111], v[128:131], v[178:181], v[108:111]
	v_mfma_f32_16x16x32_bf16 v[104:107], v[152:155], v[178:181], v[104:107]
	v_mfma_f32_16x16x32_bf16 v[92:95], v[128:131], v[186:189], v[92:95]
	v_mfma_f32_16x16x32_bf16 v[88:91], v[152:155], v[186:189], v[88:91]
	v_mfma_f32_16x16x32_bf16 v[76:79], v[128:131], v[194:197], v[76:79]
	v_mfma_f32_16x16x32_bf16 v[72:75], v[152:155], v[194:197], v[72:75]
	v_mfma_f32_16x16x32_bf16 v[124:127], v[132:135], v[174:177], v[124:127]
	v_mfma_f32_16x16x32_bf16 v[120:123], v[156:159], v[174:177], v[120:123]
	v_mfma_f32_16x16x32_bf16 v[108:111], v[132:135], v[182:185], v[108:111]
	v_mfma_f32_16x16x32_bf16 v[104:107], v[156:159], v[182:185], v[104:107]
	v_mfma_f32_16x16x32_bf16 v[92:95], v[132:135], v[190:193], v[92:95]
	v_mfma_f32_16x16x32_bf16 v[88:91], v[156:159], v[190:193], v[88:91]
	v_mfma_f32_16x16x32_bf16 v[76:79], v[132:135], v[198:201], v[76:79]
	v_mfma_f32_16x16x32_bf16 v[72:75], v[156:159], v[198:201], v[72:75]
	s_setprio 0
	s_barrier
	s_add_i32 s18, 16, 0x1c000
	s_add_i32 s19, s82, s5
	v_add_u32_e32 v214, s18, v166
	v_lshl_add_u64 v[218:219], v[218:219], 0, s[24:25]
	s_mov_b32 m0, s19
	ds_read_b128 v[202:205], v214
	ds_read_b128 v[206:209], v214 offset:1024
	ds_read_b128 v[210:213], v214 offset:2048
	ds_read_b128 v[214:217], v214 offset:3072
	global_load_lds_dwordx4 v[218:219], off
	v_lshl_add_u64 v[218:219], v[220:221], 0, s[24:25]
	s_add_i32 m0, s19, 0x2000
	s_nop 0
	global_load_lds_dwordx4 v[218:219], off
	s_barrier
	s_waitcnt lgkmcnt(0)
	s_setprio 1
	s_waitcnt lgkmcnt(0)
	v_mfma_f32_16x16x32_bf16 v[116:119], v[202:205], v[160:163], v[116:119]
	v_mfma_f32_16x16x32_bf16 v[112:115], v[210:213], v[160:163], v[112:115]
	v_mfma_f32_16x16x32_bf16 v[100:103], v[202:205], v[178:181], v[100:103]
	v_mfma_f32_16x16x32_bf16 v[96:99], v[210:213], v[178:181], v[96:99]
	v_mfma_f32_16x16x32_bf16 v[84:87], v[202:205], v[186:189], v[84:87]
	v_mfma_f32_16x16x32_bf16 v[80:83], v[210:213], v[186:189], v[80:83]
	v_mfma_f32_16x16x32_bf16 v[68:71], v[202:205], v[194:197], v[68:71]
	v_mfma_f32_16x16x32_bf16 v[64:67], v[210:213], v[194:197], v[64:67]
	v_mfma_f32_16x16x32_bf16 v[116:119], v[206:209], v[174:177], v[116:119]
	v_mfma_f32_16x16x32_bf16 v[112:115], v[214:217], v[174:177], v[112:115]
	v_mfma_f32_16x16x32_bf16 v[100:103], v[206:209], v[182:185], v[100:103]
	v_mfma_f32_16x16x32_bf16 v[96:99], v[214:217], v[182:185], v[96:99]
	v_mfma_f32_16x16x32_bf16 v[84:87], v[206:209], v[190:193], v[84:87]
	v_mfma_f32_16x16x32_bf16 v[80:83], v[214:217], v[190:193], v[80:83]
	v_mfma_f32_16x16x32_bf16 v[68:71], v[206:209], v[198:201], v[68:71]
	v_mfma_f32_16x16x32_bf16 v[64:67], v[214:217], v[198:201], v[64:67]
	s_setprio 0
	s_mov_b32 m0, s56
	v_lshl_add_u64 v[218:219], v[222:223], 0, s[24:25]
	s_barrier
	ds_read_b128 v[160:163], v171 offset:49152
	ds_read_b128 v[174:177], v171 offset:50176
	ds_read_b128 v[178:181], v171 offset:51200
	ds_read_b128 v[182:185], v171 offset:52224
	ds_read_b128 v[186:189], v171 offset:53248
	ds_read_b128 v[190:193], v171 offset:54272
	ds_read_b128 v[194:197], v171 offset:55296
	ds_read_b128 v[198:201], v171 offset:56320
	global_load_lds_dwordx4 v[218:219], off
	v_lshl_add_u64 v[218:219], v[224:225], 0, s[24:25]
	s_mov_b32 m0, s57
	s_nop 0
	global_load_lds_dwordx4 v[218:219], off
	s_barrier
	s_waitcnt lgkmcnt(0)
	s_setprio 1
	s_waitcnt lgkmcnt(0)
	v_mfma_f32_16x16x32_bf16 v[60:63], v[128:131], v[160:163], v[60:63]
	v_mfma_f32_16x16x32_bf16 v[56:59], v[152:155], v[160:163], v[56:59]
	v_mfma_f32_16x16x32_bf16 v[44:47], v[128:131], v[178:181], v[44:47]
	v_mfma_f32_16x16x32_bf16 v[40:43], v[152:155], v[178:181], v[40:43]
	v_mfma_f32_16x16x32_bf16 v[28:31], v[128:131], v[186:189], v[28:31]
	v_mfma_f32_16x16x32_bf16 v[24:27], v[152:155], v[186:189], v[24:27]
	v_mfma_f32_16x16x32_bf16 v[12:15], v[128:131], v[194:197], v[12:15]
	v_mfma_f32_16x16x32_bf16 v[8:11], v[152:155], v[194:197], v[8:11]
	v_mfma_f32_16x16x32_bf16 v[60:63], v[132:135], v[174:177], v[60:63]
	v_mfma_f32_16x16x32_bf16 v[56:59], v[156:159], v[174:177], v[56:59]
	v_mfma_f32_16x16x32_bf16 v[44:47], v[132:135], v[182:185], v[44:47]
	v_mfma_f32_16x16x32_bf16 v[40:43], v[156:159], v[182:185], v[40:43]
	v_mfma_f32_16x16x32_bf16 v[28:31], v[132:135], v[190:193], v[28:31]
	v_mfma_f32_16x16x32_bf16 v[24:27], v[156:159], v[190:193], v[24:27]
	v_mfma_f32_16x16x32_bf16 v[12:15], v[132:135], v[198:201], v[12:15]
	v_mfma_f32_16x16x32_bf16 v[8:11], v[156:159], v[198:201], v[8:11]
	s_setprio 0
	s_barrier
	s_add_u32 s16, s16, 0x80080
	s_addc_u32 s17, s17, 0
	s_add_i32 s18, s18, s5
	v_lshl_add_u64 v[128:129], s[16:17], 0, v[138:139]
	s_mov_b32 m0, s18
	s_nop 0
	global_load_lds_dwordx4 v[128:129], off
	v_lshl_add_u64 v[128:129], s[16:17], 0, v[140:141]
	s_add_i32 m0, s18, 0x2000
	s_nop 0
	global_load_lds_dwordx4 v[128:129], off
	s_waitcnt vmcnt(6)
	s_barrier
	s_setprio 1
	v_mfma_f32_16x16x32_bf16 v[52:55], v[202:205], v[160:163], v[52:55]
	v_mfma_f32_16x16x32_bf16 v[48:51], v[210:213], v[160:163], v[48:51]
	v_mfma_f32_16x16x32_bf16 v[36:39], v[202:205], v[178:181], v[36:39]
	v_mfma_f32_16x16x32_bf16 v[32:35], v[210:213], v[178:181], v[32:35]
	v_mfma_f32_16x16x32_bf16 v[20:23], v[202:205], v[186:189], v[20:23]
	v_mfma_f32_16x16x32_bf16 v[16:19], v[210:213], v[186:189], v[16:19]
	v_mfma_f32_16x16x32_bf16 v[4:7], v[202:205], v[194:197], v[4:7]
	v_mfma_f32_16x16x32_bf16 v[0:3], v[210:213], v[194:197], v[0:3]
	v_mfma_f32_16x16x32_bf16 v[52:55], v[206:209], v[174:177], v[52:55]
	v_mfma_f32_16x16x32_bf16 v[48:51], v[214:217], v[174:177], v[48:51]
	v_mfma_f32_16x16x32_bf16 v[36:39], v[206:209], v[182:185], v[36:39]
	v_mfma_f32_16x16x32_bf16 v[32:35], v[214:217], v[182:185], v[32:35]
	v_mfma_f32_16x16x32_bf16 v[20:23], v[206:209], v[190:193], v[20:23]
	v_mfma_f32_16x16x32_bf16 v[16:19], v[214:217], v[190:193], v[16:19]
	v_mfma_f32_16x16x32_bf16 v[4:7], v[206:209], v[198:201], v[4:7]
	v_mfma_f32_16x16x32_bf16 v[0:3], v[214:217], v[198:201], v[0:3]
	s_setprio 0
	s_add_i32 s81, s81, 2
	s_add_u32 s14, s14, 0x100
	s_addc_u32 s15, s15, 0
	s_add_u32 s68, s68, 0x100
	s_addc_u32 s69, s69, 0
	s_cmp_gt_u32 s81, 29
	s_barrier
	s_cbranch_scc0 .LBB0_107
	s_lshl_b32 s49, s8, 8
	v_add_u32_e32 v160, s49, v164
	v_ashrrev_i32_e32 v161, 31, v160
	v_lshl_add_u64 v[162:163], v[160:161], 2, s[22:23]
	global_load_dword v152, v[162:163], off offset:0
	global_load_dword v153, v[162:163], off offset:64
	global_load_dword v154, v[162:163], off offset:128
	global_load_dword v155, v[162:163], off offset:192
	global_load_dword v156, v[162:163], off offset:512
	global_load_dword v157, v[162:163], off offset:576
	global_load_dword v158, v[162:163], off offset:640
	global_load_dword v159, v[162:163], off offset:704
	s_cmp_lt_i32 s12, 24
	s_cselect_b64 s[14:15], -1, 0
	s_and_b64 s[14:15], s[14:15], s[44:45]
	s_cmp_lt_i32 s12, 12
	s_cselect_b32 s13, s46, 1.0
	v_mov_b32_e32 v236, s13
	v_mov_b64_e32 v[162:163], s[50:51]
	v_mad_i64_i32 v[162:163], s[16:17], v160, s76, v[162:163]
	s_lshl_b32 s68, s12, 9
	s_mov_b32 s69, 0
	v_lshl_add_u64 v[162:163], v[162:163], 0, s[68:69]
	v_lshl_add_u64 v[162:163], v[162:163], 0, s[42:43]
	v_and_b32_e32 v235, 8, v165
	v_mad_u32_u24 v235, v235, 3, v165
	v_mov_b32_e32 v238, 0
	v_mov_b32_e32 v239, v238
	v_mov_b32_e32 v238, v235
	v_lshl_add_u64 v[162:163], v[162:163], 0, v[238:239]
	s_mov_b32 s68, 0x48000
	s_mov_b32 s82, 0x168000
	s_mov_b32 s83, 0
	s_and_b64 vcc, exec, s[14:15]
	s_cbranch_vccz .Lq0_noropeld
	v_lshlrev_b32_e32 v230, 5, v160
	v_and_or_b32 v230, v230, s79, v165
	v_lshlrev_b32_e32 v230, 2, v230
	v_add_u32_e32 v231, 0x1000, v230
	v_add_u32_e32 v233, 0x4000, v230
	v_add_u32_e32 v234, 0x5000, v230
	global_load_dwordx4 v[174:177], v230, s[58:59] offset:0
	global_load_dwordx4 v[178:181], v230, s[58:59] offset:16
	global_load_dwordx4 v[182:185], v230, s[58:59] offset:2048
	global_load_dwordx4 v[186:189], v230, s[58:59] offset:2064
	global_load_dwordx4 v[190:193], v231, s[58:59] offset:0
	global_load_dwordx4 v[194:197], v231, s[58:59] offset:16
	global_load_dwordx4 v[198:201], v231, s[58:59] offset:2048
	global_load_dwordx4 v[202:205], v231, s[58:59] offset:2064
	global_load_dwordx4 v[206:209], v233, s[58:59] offset:0
	global_load_dwordx4 v[210:213], v233, s[58:59] offset:16
	global_load_dwordx4 v[214:217], v233, s[58:59] offset:2048
	global_load_dwordx4 v[218:221], v233, s[58:59] offset:2064
	global_load_dwordx4 v[222:225], v234, s[58:59] offset:0
	global_load_dwordx4 v[226:229], v234, s[58:59] offset:16
	global_load_dwordx4 v[128:131], v234, s[58:59] offset:2048
	global_load_dwordx4 v[132:135], v234, s[58:59] offset:2064

.Lq0_norope_0:
	v_pk_mul_f32 v[124:125], v[124:125], v[236:237] op_sel_hi:[1,0]
	v_pk_mul_f32 v[126:127], v[126:127], v[236:237] op_sel_hi:[1,0]
	v_pk_mul_f32 v[120:121], v[120:121], v[236:237] op_sel_hi:[1,0]
	v_pk_mul_f32 v[122:123], v[122:123], v[236:237] op_sel_hi:[1,0]
	v_pk_mul_f32 v[116:117], v[116:117], v[236:237] op_sel_hi:[1,0]
	v_pk_mul_f32 v[118:119], v[118:119], v[236:237] op_sel_hi:[1,0]
	v_pk_mul_f32 v[112:113], v[112:113], v[236:237] op_sel_hi:[1,0]
	v_pk_mul_f32 v[114:115], v[114:115], v[236:237] op_sel_hi:[1,0]
	v_cvt_pk_bf16_f32 v124, v124, v125
	v_cvt_pk_bf16_f32 v125, v126, v127
	v_cvt_pk_bf16_f32 v126, v120, v121
	v_cvt_pk_bf16_f32 v127, v122, v123
	v_cvt_pk_bf16_f32 v116, v116, v117
	v_cvt_pk_bf16_f32 v117, v118, v119
	v_cvt_pk_bf16_f32 v118, v112, v113
	v_cvt_pk_bf16_f32 v119, v114, v115
	s_nop 1
	v_permlane16_swap_b32_e32 v124, v126
	v_permlane16_swap_b32_e32 v125, v127
	v_permlane16_swap_b32_e32 v116, v118
	v_permlane16_swap_b32_e32 v117, v119
	global_store_dwordx4 v[162:163], v[124:127], off offset:0
	global_store_dwordx4 v[162:163], v[116:119], off offset:256
	v_lshl_add_u64 v[162:163], v[162:163], 0, s[68:69]
	v_pk_mul_f32 v[108:109], v[108:109], v[152:153] op_sel:[0,1] op_sel_hi:[1,1]
	v_pk_mul_f32 v[110:111], v[110:111], v[152:153] op_sel:[0,1] op_sel_hi:[1,1]
	v_pk_mul_f32 v[104:105], v[104:105], v[152:153] op_sel:[0,1] op_sel_hi:[1,1]
	v_pk_mul_f32 v[106:107], v[106:107], v[152:153] op_sel:[0,1] op_sel_hi:[1,1]
	v_pk_mul_f32 v[100:101], v[100:101], v[152:153] op_sel:[0,1] op_sel_hi:[1,1]
	v_pk_mul_f32 v[102:103], v[102:103], v[152:153] op_sel:[0,1] op_sel_hi:[1,1]
	v_pk_mul_f32 v[96:97], v[96:97], v[152:153] op_sel:[0,1] op_sel_hi:[1,1]
	v_pk_mul_f32 v[98:99], v[98:99], v[152:153] op_sel:[0,1] op_sel_hi:[1,1]
	s_and_b64 vcc, exec, s[14:15]
	s_cbranch_vccz .Lq0_norope_1
	v_mul_f32_e32 v230, v104, v183
	v_mul_f32_e32 v231, v108, v183
	v_fma_f32 v108, v108, v182, -v230
	v_fma_f32 v104, v104, v182, v231
	v_mul_f32_e32 v233, v105, v185
	v_mul_f32_e32 v234, v109, v185
	v_fma_f32 v109, v109, v184, -v233
	v_fma_f32 v105, v105, v184, v234
	v_mul_f32_e32 v230, v106, v187
	v_mul_f32_e32 v231, v110, v187
	v_fma_f32 v110, v110, v186, -v230
	v_fma_f32 v106, v106, v186, v231
	v_mul_f32_e32 v233, v107, v189
	v_mul_f32_e32 v234, v111, v189
	v_fma_f32 v111, v111, v188, -v233
	v_fma_f32 v107, v107, v188, v234
	v_mul_f32_e32 v230, v96, v183
	v_mul_f32_e32 v231, v100, v183
	v_fma_f32 v100, v100, v182, -v230
	v_fma_f32 v96, v96, v182, v231
	v_mul_f32_e32 v233, v97, v185
	v_mul_f32_e32 v234, v101, v185
	v_fma_f32 v101, v101, v184, -v233
	v_fma_f32 v97, v97, v184, v234
	v_mul_f32_e32 v230, v98, v187
	v_mul_f32_e32 v231, v102, v187
	v_fma_f32 v102, v102, v186, -v230
	v_fma_f32 v98, v98, v186, v231
	v_mul_f32_e32 v233, v99, v189
	v_mul_f32_e32 v234, v103, v189
	v_fma_f32 v103, v103, v188, -v233
	v_fma_f32 v99, v99, v188, v234
.Lq0_norope_1:
	v_pk_mul_f32 v[108:109], v[108:109], v[236:237] op_sel_hi:[1,0]
	v_pk_mul_f32 v[110:111], v[110:111], v[236:237] op_sel_hi:[1,0]
	v_pk_mul_f32 v[104:105], v[104:105], v[236:237] op_sel_hi:[1,0]
	v_pk_mul_f32 v[106:107], v[106:107], v[236:237] op_sel_hi:[1,0]
	v_pk_mul_f32 v[100:101], v[100:101], v[236:237] op_sel_hi:[1,0]
	v_pk_mul_f32 v[102:103], v[102:103], v[236:237] op_sel_hi:[1,0]
	v_pk_mul_f32 v[96:97], v[96:97], v[236:237] op_sel_hi:[1,0]
	v_pk_mul_f32 v[98:99], v[98:99], v[236:237] op_sel_hi:[1,0]
	v_cvt_pk_bf16_f32 v108, v108, v109
	v_cvt_pk_bf16_f32 v109, v110, v111
	v_cvt_pk_bf16_f32 v110, v104, v105
	v_cvt_pk_bf16_f32 v111, v106, v107
	v_cvt_pk_bf16_f32 v100, v100, v101
	v_cvt_pk_bf16_f32 v101, v102, v103
	v_cvt_pk_bf16_f32 v102, v96, v97
	v_cvt_pk_bf16_f32 v103, v98, v99
	s_nop 1
	v_permlane16_swap_b32_e32 v108, v110
	v_permlane16_swap_b32_e32 v109, v111
	v_permlane16_swap_b32_e32 v100, v102
	v_permlane16_swap_b32_e32 v101, v103
	global_store_dwordx4 v[162:163], v[108:111], off offset:0
	global_store_dwordx4 v[162:163], v[100:103], off offset:256
	v_lshl_add_u64 v[162:163], v[162:163], 0, s[68:69]
	v_pk_mul_f32 v[92:93], v[92:93], v[154:155] op_sel:[0,0] op_sel_hi:[1,0]
	v_pk_mul_f32 v[94:95], v[94:95], v[154:155] op_sel:[0,0] op_sel_hi:[1,0]
	v_pk_mul_f32 v[88:89], v[88:89], v[154:155] op_sel:[0,0] op_sel_hi:[1,0]
	v_pk_mul_f32 v[90:91], v[90:91], v[154:155] op_sel:[0,0] op_sel_hi:[1,0]
	v_pk_mul_f32 v[84:85], v[84:85], v[154:155] op_sel:[0,0] op_sel_hi:[1,0]
	v_pk_mul_f32 v[86:87], v[86:87], v[154:155] op_sel:[0,0] op_sel_hi:[1,0]
	v_pk_mul_f32 v[80:81], v[80:81], v[154:155] op_sel:[0,0] op_sel_hi:[1,0]
	v_pk_mul_f32 v[82:83], v[82:83], v[154:155] op_sel:[0,0] op_sel_hi:[1,0]
	s_and_b64 vcc, exec, s[14:15]
	s_cbranch_vccz .Lq0_norope_2
	v_mul_f32_e32 v230, v88, v191
	v_mul_f32_e32 v231, v92, v191
	v_fma_f32 v92, v92, v190, -v230
	v_fma_f32 v88, v88, v190, v231
	v_mul_f32_e32 v233, v89, v193
	v_mul_f32_e32 v234, v93, v193
	v_fma_f32 v93, v93, v192, -v233
	v_fma_f32 v89, v89, v192, v234
	v_mul_f32_e32 v230, v90, v195
	v_mul_f32_e32 v231, v94, v195
	v_fma_f32 v94, v94, v194, -v230
	v_fma_f32 v90, v90, v194, v231
	v_mul_f32_e32 v233, v91, v197
	v_mul_f32_e32 v234, v95, v197
	v_fma_f32 v95, v95, v196, -v233
	v_fma_f32 v91, v91, v196, v234
	v_mul_f32_e32 v230, v80, v191
	v_mul_f32_e32 v231, v84, v191
	v_fma_f32 v84, v84, v190, -v230
	v_fma_f32 v80, v80, v190, v231
	v_mul_f32_e32 v233, v81, v193
	v_mul_f32_e32 v234, v85, v193
	v_fma_f32 v85, v85, v192, -v233
	v_fma_f32 v81, v81, v192, v234
	v_mul_f32_e32 v230, v82, v195
	v_mul_f32_e32 v231, v86, v195
	v_fma_f32 v86, v86, v194, -v230
	v_fma_f32 v82, v82, v194, v231
	v_mul_f32_e32 v233, v83, v197
	v_mul_f32_e32 v234, v87, v197
	v_fma_f32 v87, v87, v196, -v233
	v_fma_f32 v83, v83, v196, v234
.Lq0_norope_2:
	v_pk_mul_f32 v[92:93], v[92:93], v[236:237] op_sel_hi:[1,0]
	v_pk_mul_f32 v[94:95], v[94:95], v[236:237] op_sel_hi:[1,0]
	v_pk_mul_f32 v[88:89], v[88:89], v[236:237] op_sel_hi:[1,0]
	v_pk_mul_f32 v[90:91], v[90:91], v[236:237] op_sel_hi:[1,0]
	v_pk_mul_f32 v[84:85], v[84:85], v[236:237] op_sel_hi:[1,0]
	v_pk_mul_f32 v[86:87], v[86:87], v[236:237] op_sel_hi:[1,0]
	v_pk_mul_f32 v[80:81], v[80:81], v[236:237] op_sel_hi:[1,0]
	v_pk_mul_f32 v[82:83], v[82:83], v[236:237] op_sel_hi:[1,0]
	v_cvt_pk_bf16_f32 v92, v92, v93
	v_cvt_pk_bf16_f32 v93, v94, v95
	v_cvt_pk_bf16_f32 v94, v88, v89
	v_cvt_pk_bf16_f32 v95, v90, v91
	v_cvt_pk_bf16_f32 v84, v84, v85
	v_cvt_pk_bf16_f32 v85, v86, v87
	v_cvt_pk_bf16_f32 v86, v80, v81
	v_cvt_pk_bf16_f32 v87, v82, v83
	s_nop 1
	v_permlane16_swap_b32_e32 v92, v94
	v_permlane16_swap_b32_e32 v93, v95
	v_permlane16_swap_b32_e32 v84, v86
	v_permlane16_swap_b32_e32 v85, v87
	global_store_dwordx4 v[162:163], v[92:95], off offset:0
	global_store_dwordx4 v[162:163], v[84:87], off offset:256
	v_lshl_add_u64 v[162:163], v[162:163], 0, s[68:69]
	v_pk_mul_f32 v[76:77], v[76:77], v[154:155] op_sel:[0,1] op_sel_hi:[1,1]
	v_pk_mul_f32 v[78:79], v[78:79], v[154:155] op_sel:[0,1] op_sel_hi:[1,1]
	v_pk_mul_f32 v[72:73], v[72:73], v[154:155] op_sel:[0,1] op_sel_hi:[1,1]
	v_pk_mul_f32 v[74:75], v[74:75], v[154:155] op_sel:[0,1] op_sel_hi:[1,1]
	v_pk_mul_f32 v[68:69], v[68:69], v[154:155] op_sel:[0,1] op_sel_hi:[1,1]
	v_pk_mul_f32 v[70:71], v[70:71], v[154:155] op_sel:[0,1] op_sel_hi:[1,1]
	v_pk_mul_f32 v[64:65], v[64:65], v[154:155] op_sel:[0,1] op_sel_hi:[1,1]
	v_pk_mul_f32 v[66:67], v[66:67], v[154:155] op_sel:[0,1] op_sel_hi:[1,1]
	s_and_b64 vcc, exec, s[14:15]
	s_cbranch_vccz .Lq0_norope_3
	v_mul_f32_e32 v230, v72, v199
	v_mul_f32_e32 v231, v76, v199
	v_fma_f32 v76, v76, v198, -v230
	v_fma_f32 v72, v72, v198, v231
	v_mul_f32_e32 v233, v73, v201
	v_mul_f32_e32 v234, v77, v201
	v_fma_f32 v77, v77, v200, -v233
	v_fma_f32 v73, v73, v200, v234
	v_mul_f32_e32 v230, v74, v203
	v_mul_f32_e32 v231, v78, v203
	v_fma_f32 v78, v78, v202, -v230
	v_fma_f32 v74, v74, v202, v231
	v_mul_f32_e32 v233, v75, v205
	v_mul_f32_e32 v234, v79, v205
	v_fma_f32 v79, v79, v204, -v233
	v_fma_f32 v75, v75, v204, v234
	v_mul_f32_e32 v230, v64, v199
	v_mul_f32_e32 v231, v68, v199
	v_fma_f32 v68, v68, v198, -v230
	v_fma_f32 v64, v64, v198, v231
	v_mul_f32_e32 v233, v65, v201
	v_mul_f32_e32 v234, v69, v201
	v_fma_f32 v69, v69, v200, -v233
	v_fma_f32 v65, v65, v200, v234
	v_mul_f32_e32 v230, v66, v203
	v_mul_f32_e32 v231, v70, v203
	v_fma_f32 v70, v70, v202, -v230
	v_fma_f32 v66, v66, v202, v231
	v_mul_f32_e32 v233, v67, v205
	v_mul_f32_e32 v234, v71, v205
	v_fma_f32 v71, v71, v204, -v233
	v_fma_f32 v67, v67, v204, v234
.Lq0_norope_3:
	v_pk_mul_f32 v[76:77], v[76:77], v[236:237] op_sel_hi:[1,0]
	v_pk_mul_f32 v[78:79], v[78:79], v[236:237] op_sel_hi:[1,0]
	v_pk_mul_f32 v[72:73], v[72:73], v[236:237] op_sel_hi:[1,0]
	v_pk_mul_f32 v[74:75], v[74:75], v[236:237] op_sel_hi:[1,0]
	v_pk_mul_f32 v[68:69], v[68:69], v[236:237] op_sel_hi:[1,0]
	v_pk_mul_f32 v[70:71], v[70:71], v[236:237] op_sel_hi:[1,0]
	v_pk_mul_f32 v[64:65], v[64:65], v[236:237] op_sel_hi:[1,0]
	v_pk_mul_f32 v[66:67], v[66:67], v[236:237] op_sel_hi:[1,0]
	v_cvt_pk_bf16_f32 v76, v76, v77
	v_cvt_pk_bf16_f32 v77, v78, v79
	v_cvt_pk_bf16_f32 v78, v72, v73
	v_cvt_pk_bf16_f32 v79, v74, v75
	v_cvt_pk_bf16_f32 v68, v68, v69
	v_cvt_pk_bf16_f32 v69, v70, v71
	v_cvt_pk_bf16_f32 v70, v64, v65
	v_cvt_pk_bf16_f32 v71, v66, v67
	s_nop 1
	v_permlane16_swap_b32_e32 v76, v78
	v_permlane16_swap_b32_e32 v77, v79
	v_permlane16_swap_b32_e32 v68, v70
	v_permlane16_swap_b32_e32 v69, v71
	global_store_dwordx4 v[162:163], v[76:79], off offset:0
	global_store_dwordx4 v[162:163], v[68:71], off offset:256
	v_lshl_add_u64 v[162:163], v[162:163], 0, s[82:83]
	v_pk_mul_f32 v[60:61], v[60:61], v[156:157] op_sel:[0,0] op_sel_hi:[1,0]
	v_pk_mul_f32 v[62:63], v[62:63], v[156:157] op_sel:[0,0] op_sel_hi:[1,0]
	v_pk_mul_f32 v[56:57], v[56:57], v[156:157] op_sel:[0,0] op_sel_hi:[1,0]
	v_pk_mul_f32 v[58:59], v[58:59], v[156:157] op_sel:[0,0] op_sel_hi:[1,0]
	v_pk_mul_f32 v[52:53], v[52:53], v[156:157] op_sel:[0,0] op_sel_hi:[1,0]
	v_pk_mul_f32 v[54:55], v[54:55], v[156:157] op_sel:[0,0] op_sel_hi:[1,0]
	v_pk_mul_f32 v[48:49], v[48:49], v[156:157] op_sel:[0,0] op_sel_hi:[1,0]
	v_pk_mul_f32 v[50:51], v[50:51], v[156:157] op_sel:[0,0] op_sel_hi:[1,0]
	s_and_b64 vcc, exec, s[14:15]
	s_cbranch_vccz .Lq0_norope_4
	v_mul_f32_e32 v230, v56, v207
	v_mul_f32_e32 v231, v60, v207
	v_fma_f32 v60, v60, v206, -v230
	v_fma_f32 v56, v56, v206, v231
	v_mul_f32_e32 v233, v57, v209
	v_mul_f32_e32 v234, v61, v209
	v_fma_f32 v61, v61, v208, -v233
	v_fma_f32 v57, v57, v208, v234
	v_mul_f32_e32 v230, v58, v211
	v_mul_f32_e32 v231, v62, v211
	v_fma_f32 v62, v62, v210, -v230
	v_fma_f32 v58, v58, v210, v231
	v_mul_f32_e32 v233, v59, v213
	v_mul_f32_e32 v234, v63, v213
	v_fma_f32 v63, v63, v212, -v233
	v_fma_f32 v59, v59, v212, v234
	v_mul_f32_e32 v230, v48, v207
	v_mul_f32_e32 v231, v52, v207
	v_fma_f32 v52, v52, v206, -v230
	v_fma_f32 v48, v48, v206, v231
	v_mul_f32_e32 v233, v49, v209
	v_mul_f32_e32 v234, v53, v209
	v_fma_f32 v53, v53, v208, -v233
	v_fma_f32 v49, v49, v208, v234
	v_mul_f32_e32 v230, v50, v211
	v_mul_f32_e32 v231, v54, v211
	v_fma_f32 v54, v54, v210, -v230
	v_fma_f32 v50, v50, v210, v231
	v_mul_f32_e32 v233, v51, v213
	v_mul_f32_e32 v234, v55, v213
	v_fma_f32 v55, v55, v212, -v233
	v_fma_f32 v51, v51, v212, v234
.Lq0_norope_4:
	v_pk_mul_f32 v[60:61], v[60:61], v[236:237] op_sel_hi:[1,0]
	v_pk_mul_f32 v[62:63], v[62:63], v[236:237] op_sel_hi:[1,0]
	v_pk_mul_f32 v[56:57], v[56:57], v[236:237] op_sel_hi:[1,0]
	v_pk_mul_f32 v[58:59], v[58:59], v[236:237] op_sel_hi:[1,0]
	v_pk_mul_f32 v[52:53], v[52:53], v[236:237] op_sel_hi:[1,0]
	v_pk_mul_f32 v[54:55], v[54:55], v[236:237] op_sel_hi:[1,0]
	v_pk_mul_f32 v[48:49], v[48:49], v[236:237] op_sel_hi:[1,0]
	v_pk_mul_f32 v[50:51], v[50:51], v[236:237] op_sel_hi:[1,0]
	v_cvt_pk_bf16_f32 v60, v60, v61
	v_cvt_pk_bf16_f32 v61, v62, v63
	v_cvt_pk_bf16_f32 v62, v56, v57
	v_cvt_pk_bf16_f32 v63, v58, v59
	v_cvt_pk_bf16_f32 v52, v52, v53
	v_cvt_pk_bf16_f32 v53, v54, v55
	v_cvt_pk_bf16_f32 v54, v48, v49
	v_cvt_pk_bf16_f32 v55, v50, v51
	s_nop 1
	v_permlane16_swap_b32_e32 v60, v62
	v_permlane16_swap_b32_e32 v61, v63
	v_permlane16_swap_b32_e32 v52, v54
	v_permlane16_swap_b32_e32 v53, v55
	global_store_dwordx4 v[162:163], v[60:63], off offset:0
	global_store_dwordx4 v[162:163], v[52:55], off offset:256
	v_lshl_add_u64 v[162:163], v[162:163], 0, s[68:69]
	v_pk_mul_f32 v[44:45], v[44:45], v[156:157] op_sel:[0,1] op_sel_hi:[1,1]
	v_pk_mul_f32 v[46:47], v[46:47], v[156:157] op_sel:[0,1] op_sel_hi:[1,1]
	v_pk_mul_f32 v[40:41], v[40:41], v[156:157] op_sel:[0,1] op_sel_hi:[1,1]
	v_pk_mul_f32 v[42:43], v[42:43], v[156:157] op_sel:[0,1] op_sel_hi:[1,1]
	v_pk_mul_f32 v[36:37], v[36:37], v[156:157] op_sel:[0,1] op_sel_hi:[1,1]
	v_pk_mul_f32 v[38:39], v[38:39], v[156:157] op_sel:[0,1] op_sel_hi:[1,1]
	v_pk_mul_f32 v[32:33], v[32:33], v[156:157] op_sel:[0,1] op_sel_hi:[1,1]
	v_pk_mul_f32 v[34:35], v[34:35], v[156:157] op_sel:[0,1] op_sel_hi:[1,1]
	s_and_b64 vcc, exec, s[14:15]
	s_cbranch_vccz .Lq0_norope_5
	v_mul_f32_e32 v230, v40, v215
	v_mul_f32_e32 v231, v44, v215
	v_fma_f32 v44, v44, v214, -v230
	v_fma_f32 v40, v40, v214, v231
	v_mul_f32_e32 v233, v41, v217
	v_mul_f32_e32 v234, v45, v217
	v_fma_f32 v45, v45, v216, -v233
	v_fma_f32 v41, v41, v216, v234
	v_mul_f32_e32 v230, v42, v219
	v_mul_f32_e32 v231, v46, v219
	v_fma_f32 v46, v46, v218, -v230
	v_fma_f32 v42, v42, v218, v231
	v_mul_f32_e32 v233, v43, v221
	v_mul_f32_e32 v234, v47, v221
	v_fma_f32 v47, v47, v220, -v233
	v_fma_f32 v43, v43, v220, v234
	v_mul_f32_e32 v230, v32, v215
	v_mul_f32_e32 v231, v36, v215
	v_fma_f32 v36, v36, v214, -v230
	v_fma_f32 v32, v32, v214, v231
	v_mul_f32_e32 v233, v33, v217
	v_mul_f32_e32 v234, v37, v217
	v_fma_f32 v37, v37, v216, -v233
	v_fma_f32 v33, v33, v216, v234
	v_mul_f32_e32 v230, v34, v219
	v_mul_f32_e32 v231, v38, v219
	v_fma_f32 v38, v38, v218, -v230
	v_fma_f32 v34, v34, v218, v231
	v_mul_f32_e32 v233, v35, v221
	v_mul_f32_e32 v234, v39, v221
	v_fma_f32 v39, v39, v220, -v233
	v_fma_f32 v35, v35, v220, v234
.Lq0_norope_5:
	v_pk_mul_f32 v[44:45], v[44:45], v[236:237] op_sel_hi:[1,0]
	v_pk_mul_f32 v[46:47], v[46:47], v[236:237] op_sel_hi:[1,0]
	v_pk_mul_f32 v[40:41], v[40:41], v[236:237] op_sel_hi:[1,0]
	v_pk_mul_f32 v[42:43], v[42:43], v[236:237] op_sel_hi:[1,0]
	v_pk_mul_f32 v[36:37], v[36:37], v[236:237] op_sel_hi:[1,0]
	v_pk_mul_f32 v[38:39], v[38:39], v[236:237] op_sel_hi:[1,0]
	v_pk_mul_f32 v[32:33], v[32:33], v[236:237] op_sel_hi:[1,0]
	v_pk_mul_f32 v[34:35], v[34:35], v[236:237] op_sel_hi:[1,0]
	v_cvt_pk_bf16_f32 v44, v44, v45
	v_cvt_pk_bf16_f32 v45, v46, v47
	v_cvt_pk_bf16_f32 v46, v40, v41
	v_cvt_pk_bf16_f32 v47, v42, v43
	v_cvt_pk_bf16_f32 v36, v36, v37
	v_cvt_pk_bf16_f32 v37, v38, v39
	v_cvt_pk_bf16_f32 v38, v32, v33
	v_cvt_pk_bf16_f32 v39, v34, v35
	s_nop 1
	v_permlane16_swap_b32_e32 v44, v46
	v_permlane16_swap_b32_e32 v45, v47
	v_permlane16_swap_b32_e32 v36, v38
	v_permlane16_swap_b32_e32 v37, v39
	global_store_dwordx4 v[162:163], v[44:47], off offset:0
	global_store_dwordx4 v[162:163], v[36:39], off offset:256
	v_lshl_add_u64 v[162:163], v[162:163], 0, s[68:69]
	v_pk_mul_f32 v[28:29], v[28:29], v[158:159] op_sel:[0,0] op_sel_hi:[1,0]
	v_pk_mul_f32 v[30:31], v[30:31], v[158:159] op_sel:[0,0] op_sel_hi:[1,0]
	v_pk_mul_f32 v[24:25], v[24:25], v[158:159] op_sel:[0,0] op_sel_hi:[1,0]
	v_pk_mul_f32 v[26:27], v[26:27], v[158:159] op_sel:[0,0] op_sel_hi:[1,0]
	v_pk_mul_f32 v[20:21], v[20:21], v[158:159] op_sel:[0,0] op_sel_hi:[1,0]
	v_pk_mul_f32 v[22:23], v[22:23], v[158:159] op_sel:[0,0] op_sel_hi:[1,0]
	v_pk_mul_f32 v[16:17], v[16:17], v[158:159] op_sel:[0,0] op_sel_hi:[1,0]
	v_pk_mul_f32 v[18:19], v[18:19], v[158:159] op_sel:[0,0] op_sel_hi:[1,0]
	s_and_b64 vcc, exec, s[14:15]
	s_cbranch_vccz .Lq0_norope_6
	v_mul_f32_e32 v230, v24, v223
	v_mul_f32_e32 v231, v28, v223
	v_fma_f32 v28, v28, v222, -v230
	v_fma_f32 v24, v24, v222, v231
	v_mul_f32_e32 v233, v25, v225
	v_mul_f32_e32 v234, v29, v225
	v_fma_f32 v29, v29, v224, -v233
	v_fma_f32 v25, v25, v224, v234
	v_mul_f32_e32 v230, v26, v227
	v_mul_f32_e32 v231, v30, v227
	v_fma_f32 v30, v30, v226, -v230
	v_fma_f32 v26, v26, v226, v231
	v_mul_f32_e32 v233, v27, v229
	v_mul_f32_e32 v234, v31, v229
	v_fma_f32 v31, v31, v228, -v233
	v_fma_f32 v27, v27, v228, v234
	v_mul_f32_e32 v230, v16, v223
	v_mul_f32_e32 v231, v20, v223
	v_fma_f32 v20, v20, v222, -v230
	v_fma_f32 v16, v16, v222, v231
	v_mul_f32_e32 v233, v17, v225
	v_mul_f32_e32 v234, v21, v225
	v_fma_f32 v21, v21, v224, -v233
	v_fma_f32 v17, v17, v224, v234
	v_mul_f32_e32 v230, v18, v227
	v_mul_f32_e32 v231, v22, v227
	v_fma_f32 v22, v22, v226, -v230
	v_fma_f32 v18, v18, v226, v231
	v_mul_f32_e32 v233, v19, v229
	v_mul_f32_e32 v234, v23, v229
	v_fma_f32 v23, v23, v228, -v233
	v_fma_f32 v19, v19, v228, v234
.Lq0_norope_6:
	v_pk_mul_f32 v[28:29], v[28:29], v[236:237] op_sel_hi:[1,0]
	v_pk_mul_f32 v[30:31], v[30:31], v[236:237] op_sel_hi:[1,0]
	v_pk_mul_f32 v[24:25], v[24:25], v[236:237] op_sel_hi:[1,0]
	v_pk_mul_f32 v[26:27], v[26:27], v[236:237] op_sel_hi:[1,0]
	v_pk_mul_f32 v[20:21], v[20:21], v[236:237] op_sel_hi:[1,0]
	v_pk_mul_f32 v[22:23], v[22:23], v[236:237] op_sel_hi:[1,0]
	v_pk_mul_f32 v[16:17], v[16:17], v[236:237] op_sel_hi:[1,0]
	v_pk_mul_f32 v[18:19], v[18:19], v[236:237] op_sel_hi:[1,0]
	v_cvt_pk_bf16_f32 v28, v28, v29
	v_cvt_pk_bf16_f32 v29, v30, v31
	v_cvt_pk_bf16_f32 v30, v24, v25
	v_cvt_pk_bf16_f32 v31, v26, v27
	v_cvt_pk_bf16_f32 v20, v20, v21
	v_cvt_pk_bf16_f32 v21, v22, v23
	v_cvt_pk_bf16_f32 v22, v16, v17
	v_cvt_pk_bf16_f32 v23, v18, v19
	s_nop 1
	v_permlane16_swap_b32_e32 v28, v30
	v_permlane16_swap_b32_e32 v29, v31
	v_permlane16_swap_b32_e32 v20, v22
	v_permlane16_swap_b32_e32 v21, v23
	global_store_dwordx4 v[162:163], v[28:31], off offset:0
	global_store_dwordx4 v[162:163], v[20:23], off offset:256
	v_lshl_add_u64 v[162:163], v[162:163], 0, s[68:69]
	v_pk_mul_f32 v[12:13], v[12:13], v[158:159] op_sel:[0,1] op_sel_hi:[1,1]
	v_pk_mul_f32 v[14:15], v[14:15], v[158:159] op_sel:[0,1] op_sel_hi:[1,1]
	v_pk_mul_f32 v[8:9], v[8:9], v[158:159] op_sel:[0,1] op_sel_hi:[1,1]
	v_pk_mul_f32 v[10:11], v[10:11], v[158:159] op_sel:[0,1] op_sel_hi:[1,1]
	v_pk_mul_f32 v[4:5], v[4:5], v[158:159] op_sel:[0,1] op_sel_hi:[1,1]
	v_pk_mul_f32 v[6:7], v[6:7], v[158:159] op_sel:[0,1] op_sel_hi:[1,1]
	v_pk_mul_f32 v[0:1], v[0:1], v[158:159] op_sel:[0,1] op_sel_hi:[1,1]
	v_pk_mul_f32 v[2:3], v[2:3], v[158:159] op_sel:[0,1] op_sel_hi:[1,1]
	s_and_b64 vcc, exec, s[14:15]
	s_cbranch_vccz .Lq0_norope_7
	v_mul_f32_e32 v230, v8, v129
	v_mul_f32_e32 v231, v12, v129
	v_fma_f32 v12, v12, v128, -v230
	v_fma_f32 v8, v8, v128, v231
	v_mul_f32_e32 v233, v9, v131
	v_mul_f32_e32 v234, v13, v131
	v_fma_f32 v13, v13, v130, -v233
	v_fma_f32 v9, v9, v130, v234
	v_mul_f32_e32 v230, v10, v133
	v_mul_f32_e32 v231, v14, v133
	v_fma_f32 v14, v14, v132, -v230
	v_fma_f32 v10, v10, v132, v231
	v_mul_f32_e32 v233, v11, v135
	v_mul_f32_e32 v234, v15, v135
	v_fma_f32 v15, v15, v134, -v233
	v_fma_f32 v11, v11, v134, v234
	v_mul_f32_e32 v230, v0, v129
	v_mul_f32_e32 v231, v4, v129
	v_fma_f32 v4, v4, v128, -v230
	v_fma_f32 v0, v0, v128, v231
	v_mul_f32_e32 v233, v1, v131
	v_mul_f32_e32 v234, v5, v131
	v_fma_f32 v5, v5, v130, -v233
	v_fma_f32 v1, v1, v130, v234
	v_mul_f32_e32 v230, v2, v133
	v_mul_f32_e32 v231, v6, v133
	v_fma_f32 v6, v6, v132, -v230
	v_fma_f32 v2, v2, v132, v231
	v_mul_f32_e32 v233, v3, v135
	v_mul_f32_e32 v234, v7, v135
	v_fma_f32 v7, v7, v134, -v233
	v_fma_f32 v3, v3, v134, v234
.Lq0_norope_7:
	v_pk_mul_f32 v[12:13], v[12:13], v[236:237] op_sel_hi:[1,0]
	v_pk_mul_f32 v[14:15], v[14:15], v[236:237] op_sel_hi:[1,0]
	v_pk_mul_f32 v[8:9], v[8:9], v[236:237] op_sel_hi:[1,0]
	v_pk_mul_f32 v[10:11], v[10:11], v[236:237] op_sel_hi:[1,0]
	v_pk_mul_f32 v[4:5], v[4:5], v[236:237] op_sel_hi:[1,0]
	v_pk_mul_f32 v[6:7], v[6:7], v[236:237] op_sel_hi:[1,0]
	v_pk_mul_f32 v[0:1], v[0:1], v[236:237] op_sel_hi:[1,0]
	v_pk_mul_f32 v[2:3], v[2:3], v[236:237] op_sel_hi:[1,0]
	v_cvt_pk_bf16_f32 v12, v12, v13
	v_cvt_pk_bf16_f32 v13, v14, v15
	v_cvt_pk_bf16_f32 v14, v8, v9
	v_cvt_pk_bf16_f32 v15, v10, v11
	v_cvt_pk_bf16_f32 v4, v4, v5
	v_cvt_pk_bf16_f32 v5, v6, v7
	v_cvt_pk_bf16_f32 v6, v0, v1
	v_cvt_pk_bf16_f32 v7, v2, v3
	s_nop 1
	v_permlane16_swap_b32_e32 v12, v14
	v_permlane16_swap_b32_e32 v13, v15
	v_permlane16_swap_b32_e32 v4, v6
	v_permlane16_swap_b32_e32 v5, v7
	global_store_dwordx4 v[162:163], v[12:15], off offset:0
	global_store_dwordx4 v[162:163], v[4:7], off offset:256
	s_and_b64 vcc, exec, s[6:7]
	s_mov_b32 s12, s48
	s_mov_b32 s8, s54
	s_mov_b64 s[16:17], s[66:67]
	s_mov_b64 s[14:15], s[64:65]
	s_cbranch_vccnz .LBB0_164
	s_branch .LBB0_104
